# L2 prefetch hint of the next phase's first two weight K-tiles before the three group-local seams
# baseline (speedup 1.0000x reference)
; __device__ __forceinline__ unsigned xb_add(unsigned* p, unsigned v) { return __hip_atomic_fetch_add(p, v, __ATOMIC_RELAXED, __HIP_MEMORY_SCOPE_AGENT); }
; #define SEAM(k) do { if (IN(k) && IN((k) + 1)) GRID_SYNC(); } while (0)
; __device__ __forceinline__ void xcd_barrier(const XcdBarrier& b) {
;     asm volatile("s_waitcnt vmcnt(0)" ::: "memory");
;     __syncthreads();
;     if (threadIdx.x == 0) {
;         unsigned* bar = b.bar;
;         __builtin_amdgcn_s_waitcnt(0);
;         unsigned nloc = b.st[0], nx = b.st[1];
;         if (nloc == 0u) { xcd_barrier_complete(bar, b.x, nloc, nx); b.st[0] = nloc; b.st[1] = nx; }
;         const unsigned old = xb_add(&bar[XB_XSUB(b.x)], 1u);
; __global__ void __launch_bounds__(NTHR, 2) mk_fwd(MkArgs a) {
;     ...
;     SEAM(3);
.LBB9_444:
	v_readlane_b32 s97, v251, 39
	s_cmp_gt_i32 s93, 4
	s_cselect_b64 s[0:1], -1, 0
	s_and_b64 s[2:3], s[22:23], s[0:1]
	s_andn2_b64 vcc, exec, s[2:3]
	s_cbranch_vccnz .LBB9_498
	s_waitcnt vmcnt(0)
	s_waitcnt vmcnt(0) lgkmcnt(0)
	s_barrier
	v_mbcnt_lo_u32_b32 v252, -1, 0
	v_mbcnt_hi_u32_b32 v252, -1, v252
	s_lshr_b32 s98, s97, 6
	s_lshl_b32 s98, s98, 8
	v_lshrrev_b32_e32 v253, 1, v252
	v_and_b32_e32 v252, 1, v252
	v_add_u32_e32 v253, s98, v253
	v_mul_u32_u24_e32 v253, 0x800, v253
	v_lshl_add_u32 v252, v252, 7, v253
	s_add_u32 s98, s90, 0xe500000
	s_addc_u32 s99, s91, 0
	global_load_dword v254, v252, s[98:99]
	v_add_u32_e32 v252, 0x10000, v252
	global_load_dword v254, v252, s[98:99]
	v_add_u32_e32 v252, 0x10000, v252
	global_load_dword v254, v252, s[98:99]
	v_add_u32_e32 v252, 0x10000, v252
	global_load_dword v254, v252, s[98:99]
	v_add_u32_e32 v252, 0x10000, v252
	global_load_dword v254, v252, s[98:99]
	v_add_u32_e32 v252, 0x10000, v252
	global_load_dword v254, v252, s[98:99]
	v_add_u32_e32 v252, 0x10000, v252
	global_load_dword v254, v252, s[98:99]
	v_add_u32_e32 v252, 0x10000, v252
	global_load_dword v254, v252, s[98:99]
	s_and_saveexec_b64 s[4:5], s[80:81]
	s_cbranch_execz .LBB9_497
	v_mov_b32_e32 v0, 0x24008
	ds_read_b32 v0, v0
	s_waitcnt lgkmcnt(0)
	v_readfirstlane_b32 s98, v0
	s_nop 3
	s_cmp_eq_u32 s98, 1
	s_cbranch_scc0 .Lgb3_orig
	s_cmpk_lg_i32 s94, 0x100
	s_cbranch_scc1 .Lgb3_orig
	s_and_b32 s98, s97, 63
	s_lshl_b32 s98, s98, 2
	s_add_i32 s98, s98, 0x3f00
	v_mov_b32_e32 v0, s98
	v_mov_b32_e32 v1, 1
	global_atomic_add v0, v1, s[90:91]
	buffer_inv sc1

; __device__ __forceinline__ unsigned xb_add(unsigned* p, unsigned v) { return __hip_atomic_fetch_add(p, v, __ATOMIC_RELAXED, __HIP_MEMORY_SCOPE_AGENT); }
; #define SEAM(k) do { if (IN(k) && IN((k) + 1)) GRID_SYNC(); } while (0)
; __device__ __forceinline__ void xcd_barrier(const XcdBarrier& b) {
;     asm volatile("s_waitcnt vmcnt(0)" ::: "memory");
;     __syncthreads();
;     if (threadIdx.x == 0) {
;         unsigned* bar = b.bar;
;         __builtin_amdgcn_s_waitcnt(0);
;         unsigned nloc = b.st[0], nx = b.st[1];
;         if (nloc == 0u) { xcd_barrier_complete(bar, b.x, nloc, nx); b.st[0] = nloc; b.st[1] = nx; }
;         const unsigned old = xb_add(&bar[XB_XSUB(b.x)], 1u);
; __global__ void __launch_bounds__(NTHR, 2) mk_fwd(MkArgs a) {
;     ...
;     SEAM(4);
.LBB9_591:
	s_cmp_gt_i32 s93, 5
	s_cselect_b64 s[0:1], -1, 0
	s_and_b64 s[2:3], s[6:7], s[0:1]
	s_andn2_b64 vcc, exec, s[2:3]
	s_cbranch_vccnz .LBB9_645
	s_waitcnt vmcnt(0)
	s_waitcnt vmcnt(0) lgkmcnt(0)
	s_barrier
	v_mbcnt_lo_u32_b32 v252, -1, 0
	v_mbcnt_hi_u32_b32 v252, -1, v252
	s_lshr_b32 s98, s97, 6
	s_lshl_b32 s98, s98, 8
	v_lshrrev_b32_e32 v253, 1, v252
	v_and_b32_e32 v252, 1, v252
	v_add_u32_e32 v253, s98, v253
	v_mul_u32_u24_e32 v253, 0x800, v253
	v_lshl_add_u32 v252, v252, 7, v253
	s_add_u32 s98, s90, 0xc00000
	s_addc_u32 s99, s91, 0
	global_load_dword v254, v252, s[98:99]
	v_add_u32_e32 v252, 0x10000, v252
	global_load_dword v254, v252, s[98:99]
	v_add_u32_e32 v252, 0x10000, v252
	global_load_dword v254, v252, s[98:99]
	v_add_u32_e32 v252, 0x10000, v252
	global_load_dword v254, v252, s[98:99]
	v_add_u32_e32 v252, 0x10000, v252
	global_load_dword v254, v252, s[98:99]
	v_add_u32_e32 v252, 0x10000, v252
	global_load_dword v254, v252, s[98:99]
	v_add_u32_e32 v252, 0x10000, v252
	global_load_dword v254, v252, s[98:99]
	v_add_u32_e32 v252, 0x10000, v252
	global_load_dword v254, v252, s[98:99]
	s_and_saveexec_b64 s[4:5], s[80:81]
	s_cbranch_execz .LBB9_644
	v_mov_b32_e32 v0, 0x24008
	ds_read_b32 v0, v0
	s_waitcnt lgkmcnt(0)
	v_readfirstlane_b32 s98, v0
	s_nop 3
	s_cmp_eq_u32 s98, 1
	s_cbranch_scc0 .Lgb4_orig
	s_and_b32 s98, s97, 63
	s_lshl_b32 s98, s98, 2
	s_add_i32 s98, s98, 0x3d00
	v_mov_b32_e32 v0, s98
	v_mov_b32_e32 v1, 1
	global_atomic_add v0, v1, s[90:91]
	buffer_inv sc1

; __device__ __forceinline__ unsigned xb_add(unsigned* p, unsigned v) { return __hip_atomic_fetch_add(p, v, __ATOMIC_RELAXED, __HIP_MEMORY_SCOPE_AGENT); }
; #define SEAM(k) do { if (IN(k) && IN((k) + 1)) GRID_SYNC(); } while (0)
; __device__ __forceinline__ void xcd_barrier(const XcdBarrier& b) {
;     asm volatile("s_waitcnt vmcnt(0)" ::: "memory");
;     __syncthreads();
;     if (threadIdx.x == 0) {
;         unsigned* bar = b.bar;
;         __builtin_amdgcn_s_waitcnt(0);
;         unsigned nloc = b.st[0], nx = b.st[1];
;         if (nloc == 0u) { xcd_barrier_complete(bar, b.x, nloc, nx); b.st[0] = nloc; b.st[1] = nx; }
;         const unsigned old = xb_add(&bar[XB_XSUB(b.x)], 1u);
; __global__ void __launch_bounds__(NTHR, 2) mk_fwd(MkArgs a) {
;     ...
;     SEAM(6);
.LBB9_777:
	s_cmp_gt_i32 s93, 7
	s_cselect_b64 s[0:1], -1, 0
	s_and_b64 s[2:3], s[4:5], s[0:1]
	s_andn2_b64 vcc, exec, s[2:3]
	s_cbranch_vccnz .LBB9_831
	s_waitcnt vmcnt(0)
	s_waitcnt vmcnt(0) lgkmcnt(0)
	s_barrier
	v_mbcnt_lo_u32_b32 v252, -1, 0
	v_mbcnt_hi_u32_b32 v252, -1, v252
	s_lshr_b32 s98, s97, 6
	s_lshl_b32 s98, s98, 8
	v_lshrrev_b32_e32 v253, 1, v252
	v_and_b32_e32 v252, 1, v252
	v_add_u32_e32 v253, s98, v253
	v_mul_u32_u24_e32 v253, 0x1600, v253
	v_lshl_add_u32 v252, v252, 7, v253
	s_add_u32 s98, s90, 0x1900000
	s_addc_u32 s99, s91, 0
	global_load_dword v254, v252, s[98:99]
	v_add_u32_e32 v252, 0x2c000, v252
	global_load_dword v254, v252, s[98:99]
	v_add_u32_e32 v252, 0x2c000, v252
	global_load_dword v254, v252, s[98:99]
	v_add_u32_e32 v252, 0x2c000, v252
	global_load_dword v254, v252, s[98:99]
	v_add_u32_e32 v252, 0x2c000, v252
	global_load_dword v254, v252, s[98:99]
	v_add_u32_e32 v252, 0x2c000, v252
	global_load_dword v254, v252, s[98:99]
	v_add_u32_e32 v252, 0x2c000, v252
	global_load_dword v254, v252, s[98:99]
	v_add_u32_e32 v252, 0x2c000, v252
	global_load_dword v254, v252, s[98:99]
	s_and_saveexec_b64 s[4:5], s[80:81]
	s_cbranch_execz .LBB9_830
	v_mov_b32_e32 v0, 0x24008
	ds_read_b32 v0, v0
	s_waitcnt lgkmcnt(0)
	v_readfirstlane_b32 s98, v0
	s_nop 3
	s_cmp_eq_u32 s98, 1
	s_cbranch_scc0 .Lgb6_orig
	s_and_b32 s98, s97, 63
	s_lshl_b32 s98, s98, 2
	s_add_i32 s98, s98, 0x3e00
	v_mov_b32_e32 v0, s98
	v_mov_b32_e32 v1, 1
	global_atomic_add v0, v1, s[90:91]
	buffer_inv sc1
